# fnntld: streaming (nt) hint on the read-once bf16 loads of the final RMSNorm; on top of v90
# speedup vs baseline: 1.0027x; 1.0027x over previous
; #define GAS __attribute__((address_space(1)))
; __global__ void __launch_bounds__(NTHREADS, 2) __attribute__((amdgpu_waves_per_eu(2, 2))) hymba_fwd(Params p) {
;     ...
;         for (int row = gw; row < T_TOK; row += NGW) {
;             const GAS u32x4* yr = (const GAS u32x4*)((const GAS bf16_t*)(ws + WS_XN) + (size_t)row * 2048);
;             GAS f32x4* orow = (GAS f32x4*)((GAS float*)p.out + (size_t)row * 2048);
;             const float rs = rsqrtf(((const GAS float*)SSF)[row] * (1.0f / 2048.0f) + EPS);
; #pragma unroll
;             for (int j = 0; j < 4; ++j) {
;                 const u32x4 w = yr[lane + 64 * j];
.LBB0_772:
	v_mbcnt_lo_u32_b32 v0, -1, 0
	v_mbcnt_hi_u32_b32 v0, -1, v0
	v_readlane_b32 s0, v254, 0
	v_add_u32_e32 v0, s81, v0
	s_lshl_b32 s2, s0, 3
	v_ashrrev_i32_e32 v32, 6, v0
	v_add_u32_e32 v38, s2, v32
	s_mov_b32 s0, 0x8000
	v_cmp_gt_i32_e32 vcc, s0, v38
	s_and_saveexec_b64 s[0:1], vcc
	s_cbranch_execz .LBB0_775
	v_readlane_b32 s4, v254, 8
	v_and_b32_e32 v39, 63, v0
	v_readlane_b32 s12, v254, 16
	v_readlane_b32 s13, v254, 17
	v_readlane_b32 s14, v254, 18
	v_readlane_b32 s15, v254, 19
	v_readlane_b32 s16, v254, 20
	v_readlane_b32 s17, v254, 21
	v_lshlrev_b32_e32 v36, 5, v39
	v_mov_b32_e32 v37, 0
	v_readlane_b32 s18, v254, 22
	v_readlane_b32 s19, v254, 23
	s_mov_b64 s[12:13], s[16:17]
	v_lshl_add_u64 v[24:25], s[12:13], 0, v[36:37]
	s_mov_b64 s[0:1], 0x1000
	v_lshl_add_u64 v[26:27], v[24:25], 0, s[0:1]
	s_movk_i32 s0, 0x1000
	global_load_dwordx4 v[0:3], v36, s[12:13] offset:16
	global_load_dwordx4 v[4:7], v36, s[12:13]
	global_load_dwordx4 v[8:11], v36, s[12:13] offset:2064
	global_load_dwordx4 v[12:15], v36, s[12:13] offset:2048
	v_add_co_u32_e32 v34, vcc, s0, v24
	s_mov_b64 s[0:1], 0x1800
	s_nop 0
	v_addc_co_u32_e32 v35, vcc, 0, v25, vcc
	global_load_dwordx4 v[16:19], v[34:35], off
	global_load_dwordx4 v[20:23], v[26:27], off offset:16
	v_lshl_add_u64 v[40:41], v[24:25], 0, s[0:1]
	global_load_dwordx4 v[24:27], v[34:35], off offset:2048
	global_load_dwordx4 v[28:31], v[40:41], off offset:16
	v_ashrrev_i32_e32 v33, 31, v32
	s_ashr_i32 s3, s2, 31
	v_lshl_add_u64 v[40:41], v[32:33], 0, s[2:3]
	v_lshl_add_u64 v[32:33], v[40:41], 2, s[38:39]
	v_lshlrev_b64 v[34:35], 12, v[40:41]
	v_lshlrev_b64 v[40:41], 13, v[40:41]
	v_readlane_b32 s5, v254, 9
	v_readlane_b32 s6, v254, 10
	v_readlane_b32 s7, v254, 11
	s_mov_b64 s[14:15], s[18:19]
	s_lshl_b32 s0, s70, 3
	v_lshl_or_b32 v34, v39, 4, v34
	v_or_b32_e32 v40, v40, v36
	v_readlane_b32 s8, v254, 12
	v_readlane_b32 s9, v254, 13
	v_readlane_b32 s10, v254, 14
	v_readlane_b32 s11, v254, 15
	s_ashr_i32 s1, s0, 31
	v_lshl_add_u64 v[34:35], s[58:59], 0, v[34:35]
	s_mov_b64 s[4:5], 0xc00
	v_lshl_add_u64 v[36:37], s[14:15], 0, v[40:41]
	s_mov_b64 s[6:7], 0x1810
	s_lshl_b64 s[2:3], s[0:1], 2
	v_lshl_add_u64 v[34:35], v[34:35], 0, s[4:5]
	s_lshl_b64 s[4:5], s[0:1], 12
	v_lshl_add_u64 v[36:37], v[36:37], 0, s[6:7]
	s_lshl_b64 s[6:7], s[0:1], 13
	s_mov_b64 s[8:9], 0
	v_mov_b32_e32 v39, 0x358637bd
	s_mov_b32 s1, 0x800000
	s_movk_i32 s10, 0xf000
	s_movk_i32 s11, 0x7fff
	v_mbcnt_lo_u32_b32 v88, -1, 0
	v_mbcnt_hi_u32_b32 v88, -1, v88
	v_mov_b32_e32 v89, 0
	v_lshlrev_b32_e32 v90, 4, v88
	v_add_u32_e32 v91, 0x1000, v90
	global_load_dwordx4 v[0:3], v90, s[16:17]
	global_load_dwordx4 v[4:7], v90, s[16:17] offset:1024
	global_load_dwordx4 v[8:11], v90, s[16:17] offset:2048
	global_load_dwordx4 v[12:15], v90, s[16:17] offset:3072
	global_load_dwordx4 v[16:19], v91, s[16:17]
	global_load_dwordx4 v[20:23], v91, s[16:17] offset:1024
	global_load_dwordx4 v[24:27], v91, s[16:17] offset:2048
	global_load_dwordx4 v[28:31], v91, s[16:17] offset:3072
	v_lshlrev_b32_e32 v92, 3, v88
	v_add_u32_e32 v92, 0xc00, v92
	v_mov_b32_e32 v93, 0
	v_sub_co_u32_e32 v34, vcc, v34, v92
	s_nop 1
	v_subb_co_u32_e32 v35, vcc, v35, v93, vcc
	v_lshlrev_b32_e32 v92, 4, v88
	v_add_u32_e32 v92, 0x1810, v92
	v_sub_co_u32_e32 v36, vcc, v36, v92
	s_nop 1
	v_subb_co_u32_e32 v37, vcc, v37, v93, vcc
	v_add_co_u32_e32 v58, vcc, 0x1000, v36
	s_nop 1
	v_addc_co_u32_e32 v59, vcc, 0, v37, vcc
	s_mov_b32 s13, 8
	global_load_dword v56, v[32:33], off
	global_load_dwordx2 v[40:41], v[34:35], off nt
	global_load_dwordx2 v[42:43], v[34:35], off offset:512 nt
	global_load_dwordx2 v[44:45], v[34:35], off offset:1024 nt
	global_load_dwordx2 v[46:47], v[34:35], off offset:1536 nt
	global_load_dwordx2 v[48:49], v[34:35], off offset:2048 nt
	global_load_dwordx2 v[50:51], v[34:35], off offset:2560 nt
	global_load_dwordx2 v[52:53], v[34:35], off offset:3072 nt
	global_load_dwordx2 v[54:55], v[34:35], off offset:3584 nt
	v_lshl_add_u64 v[32:33], v[32:33], 0, s[2:3]
	v_lshl_add_u64 v[34:35], v[34:35], 0, s[4:5]
.Lfn_loop:
	global_load_dword v76, v[32:33], off
	global_load_dwordx2 v[60:61], v[34:35], off nt
	global_load_dwordx2 v[62:63], v[34:35], off offset:512 nt
	global_load_dwordx2 v[64:65], v[34:35], off offset:1024 nt
	global_load_dwordx2 v[66:67], v[34:35], off offset:1536 nt
	global_load_dwordx2 v[68:69], v[34:35], off offset:2048 nt
	global_load_dwordx2 v[70:71], v[34:35], off offset:2560 nt
	global_load_dwordx2 v[72:73], v[34:35], off offset:3072 nt
	global_load_dwordx2 v[74:75], v[34:35], off offset:3584 nt
	v_lshl_add_u64 v[32:33], v[32:33], 0, s[2:3]
	v_lshl_add_u64 v[34:35], v[34:35], 0, s[4:5]
	s_cmp_eq_u32 s13, 8
	s_cbranch_scc1 .Lfn_first
	s_waitcnt vmcnt(17)
	s_branch .Lfn_goA

; #define GAS __attribute__((address_space(1)))
; __device__ __forceinline__ float bf_lo(unsigned w) { return __uint_as_float(w << 16); }
; __device__ __forceinline__ float bf_hi(unsigned w) { return __uint_as_float(w & 0xffff0000u); }
; __global__ void __launch_bounds__(NTHREADS, 2) __attribute__((amdgpu_waves_per_eu(2, 2))) hymba_fwd(Params p) {
;     ...
;             const float rs = rsqrtf(((const GAS float*)SSF)[row] * (1.0f / 2048.0f) + EPS);
; #pragma unroll
;             for (int j = 0; j < 4; ++j) {
;                 const u32x4 w = yr[lane + 64 * j];
;                 orow[2 * (lane + 64 * j)] = (f32x4){bf_lo(w.x), bf_hi(w.x), bf_lo(w.y), bf_hi(w.y)} * rs * gf[j][0];
;                 orow[2 * (lane + 64 * j) + 1] = (f32x4){bf_lo(w.z), bf_hi(w.z), bf_lo(w.w), bf_hi(w.w)} * rs * gf[j][1];
;             }
.Lfn_goA:
	v_fmamk_f32 v78, v56, 0x3a000000, v39
	v_rsq_f32_e32 v78, v78
	v_lshlrev_b32_e32 v80, 16, v40
	v_and_b32_e32 v81, 0xffff0000, v40
	v_lshlrev_b32_e32 v82, 16, v41
	v_and_b32_e32 v83, 0xffff0000, v41
	v_pk_mul_f32 v[80:81], v[78:79], v[80:81] op_sel_hi:[0,1]
	v_pk_mul_f32 v[82:83], v[78:79], v[82:83] op_sel_hi:[0,1]
	v_pk_mul_f32 v[80:81], v[0:1], v[80:81]
	v_pk_mul_f32 v[82:83], v[2:3], v[82:83]
	global_store_dwordx4 v[36:37], v[80:83], off
	v_lshlrev_b32_e32 v84, 16, v42
	v_and_b32_e32 v85, 0xffff0000, v42
	v_lshlrev_b32_e32 v86, 16, v43
	v_and_b32_e32 v87, 0xffff0000, v43
	v_pk_mul_f32 v[84:85], v[78:79], v[84:85] op_sel_hi:[0,1]
	v_pk_mul_f32 v[86:87], v[78:79], v[86:87] op_sel_hi:[0,1]
	v_pk_mul_f32 v[84:85], v[4:5], v[84:85]
	v_pk_mul_f32 v[86:87], v[6:7], v[86:87]
	global_store_dwordx4 v[36:37], v[84:87], off offset:1024
	v_lshlrev_b32_e32 v80, 16, v44
	v_and_b32_e32 v81, 0xffff0000, v44
	v_lshlrev_b32_e32 v82, 16, v45
	v_and_b32_e32 v83, 0xffff0000, v45
	v_pk_mul_f32 v[80:81], v[78:79], v[80:81] op_sel_hi:[0,1]
	v_pk_mul_f32 v[82:83], v[78:79], v[82:83] op_sel_hi:[0,1]
	v_pk_mul_f32 v[80:81], v[8:9], v[80:81]
	v_pk_mul_f32 v[82:83], v[10:11], v[82:83]
	global_store_dwordx4 v[36:37], v[80:83], off offset:2048
	v_lshlrev_b32_e32 v84, 16, v46
	v_and_b32_e32 v85, 0xffff0000, v46
	v_lshlrev_b32_e32 v86, 16, v47
	v_and_b32_e32 v87, 0xffff0000, v47
	v_pk_mul_f32 v[84:85], v[78:79], v[84:85] op_sel_hi:[0,1]
	v_pk_mul_f32 v[86:87], v[78:79], v[86:87] op_sel_hi:[0,1]
	v_pk_mul_f32 v[84:85], v[12:13], v[84:85]
	v_pk_mul_f32 v[86:87], v[14:15], v[86:87]
	global_store_dwordx4 v[36:37], v[84:87], off offset:3072
	v_lshlrev_b32_e32 v80, 16, v48
	v_and_b32_e32 v81, 0xffff0000, v48
	v_lshlrev_b32_e32 v82, 16, v49
	v_and_b32_e32 v83, 0xffff0000, v49
	v_pk_mul_f32 v[80:81], v[78:79], v[80:81] op_sel_hi:[0,1]
	v_pk_mul_f32 v[82:83], v[78:79], v[82:83] op_sel_hi:[0,1]
	v_pk_mul_f32 v[80:81], v[16:17], v[80:81]
	v_pk_mul_f32 v[82:83], v[18:19], v[82:83]
	global_store_dwordx4 v[58:59], v[80:83], off
	v_lshlrev_b32_e32 v84, 16, v50
	v_and_b32_e32 v85, 0xffff0000, v50
	v_lshlrev_b32_e32 v86, 16, v51
	v_and_b32_e32 v87, 0xffff0000, v51
	v_pk_mul_f32 v[84:85], v[78:79], v[84:85] op_sel_hi:[0,1]
	v_pk_mul_f32 v[86:87], v[78:79], v[86:87] op_sel_hi:[0,1]
	v_pk_mul_f32 v[84:85], v[20:21], v[84:85]
	v_pk_mul_f32 v[86:87], v[22:23], v[86:87]
	global_store_dwordx4 v[58:59], v[84:87], off offset:1024
	v_lshlrev_b32_e32 v80, 16, v52
	v_and_b32_e32 v81, 0xffff0000, v52
	v_lshlrev_b32_e32 v82, 16, v53
	v_and_b32_e32 v83, 0xffff0000, v53
	v_pk_mul_f32 v[80:81], v[78:79], v[80:81] op_sel_hi:[0,1]
	v_pk_mul_f32 v[82:83], v[78:79], v[82:83] op_sel_hi:[0,1]
	v_pk_mul_f32 v[80:81], v[24:25], v[80:81]
	v_pk_mul_f32 v[82:83], v[26:27], v[82:83]
	global_store_dwordx4 v[58:59], v[80:83], off offset:2048
	v_lshlrev_b32_e32 v84, 16, v54
	v_and_b32_e32 v85, 0xffff0000, v54
	v_lshlrev_b32_e32 v86, 16, v55
	v_and_b32_e32 v87, 0xffff0000, v55
	v_pk_mul_f32 v[84:85], v[78:79], v[84:85] op_sel_hi:[0,1]
	v_pk_mul_f32 v[86:87], v[78:79], v[86:87] op_sel_hi:[0,1]
	v_pk_mul_f32 v[84:85], v[28:29], v[84:85]
	v_pk_mul_f32 v[86:87], v[30:31], v[86:87]
	global_store_dwordx4 v[58:59], v[84:87], off offset:3072
	v_lshl_add_u64 v[36:37], v[36:37], 0, s[6:7]
	v_lshl_add_u64 v[58:59], v[58:59], 0, s[6:7]
	s_cmp_eq_u32 s13, 1
	s_cbranch_scc1 .Lfn_last
; #define GAS __attribute__((address_space(1)))
; __device__ __forceinline__ float bf_lo(unsigned w) { return __uint_as_float(w << 16); }
; __device__ __forceinline__ float bf_hi(unsigned w) { return __uint_as_float(w & 0xffff0000u); }
; __global__ void __launch_bounds__(NTHREADS, 2) __attribute__((amdgpu_waves_per_eu(2, 2))) hymba_fwd(Params p) {
;     ...
;         for (int row = gw; row < T_TOK; row += NGW) {
;             const GAS u32x4* yr = (const GAS u32x4*)((const GAS bf16_t*)(ws + WS_XN) + (size_t)row * 2048);
;             GAS f32x4* orow = (GAS f32x4*)((GAS float*)p.out + (size_t)row * 2048);
;             const float rs = rsqrtf(((const GAS float*)SSF)[row] * (1.0f / 2048.0f) + EPS);
; #pragma unroll
;             for (int j = 0; j < 4; ++j) {
;                 const u32x4 w = yr[lane + 64 * j];
;                 orow[2 * (lane + 64 * j)] = (f32x4){bf_lo(w.x), bf_hi(w.x), bf_lo(w.y), bf_hi(w.y)} * rs * gf[j][0];
;                 orow[2 * (lane + 64 * j) + 1] = (f32x4){bf_lo(w.z), bf_hi(w.z), bf_lo(w.w), bf_hi(w.w)} * rs * gf[j][1];
;             }
	global_load_dword v56, v[32:33], off
	global_load_dwordx2 v[40:41], v[34:35], off nt
	global_load_dwordx2 v[42:43], v[34:35], off offset:512 nt
	global_load_dwordx2 v[44:45], v[34:35], off offset:1024 nt
	global_load_dwordx2 v[46:47], v[34:35], off offset:1536 nt
	global_load_dwordx2 v[48:49], v[34:35], off offset:2048 nt
	global_load_dwordx2 v[50:51], v[34:35], off offset:2560 nt
	global_load_dwordx2 v[52:53], v[34:35], off offset:3072 nt
	global_load_dwordx2 v[54:55], v[34:35], off offset:3584 nt
	v_lshl_add_u64 v[32:33], v[32:33], 0, s[2:3]
	v_lshl_add_u64 v[34:35], v[34:35], 0, s[4:5]
	s_waitcnt vmcnt(17)
	v_fmamk_f32 v78, v76, 0x3a000000, v39
	v_rsq_f32_e32 v78, v78
	v_lshlrev_b32_e32 v80, 16, v60
	v_and_b32_e32 v81, 0xffff0000, v60
	v_lshlrev_b32_e32 v82, 16, v61
	v_and_b32_e32 v83, 0xffff0000, v61
	v_pk_mul_f32 v[80:81], v[78:79], v[80:81] op_sel_hi:[0,1]
	v_pk_mul_f32 v[82:83], v[78:79], v[82:83] op_sel_hi:[0,1]
	v_pk_mul_f32 v[80:81], v[0:1], v[80:81]
	v_pk_mul_f32 v[82:83], v[2:3], v[82:83]
	global_store_dwordx4 v[36:37], v[80:83], off
	v_lshlrev_b32_e32 v84, 16, v62
	v_and_b32_e32 v85, 0xffff0000, v62
	v_lshlrev_b32_e32 v86, 16, v63
	v_and_b32_e32 v87, 0xffff0000, v63
	v_pk_mul_f32 v[84:85], v[78:79], v[84:85] op_sel_hi:[0,1]
	v_pk_mul_f32 v[86:87], v[78:79], v[86:87] op_sel_hi:[0,1]
	v_pk_mul_f32 v[84:85], v[4:5], v[84:85]
	v_pk_mul_f32 v[86:87], v[6:7], v[86:87]
	global_store_dwordx4 v[36:37], v[84:87], off offset:1024
	v_lshlrev_b32_e32 v80, 16, v64
	v_and_b32_e32 v81, 0xffff0000, v64
	v_lshlrev_b32_e32 v82, 16, v65
	v_and_b32_e32 v83, 0xffff0000, v65
	v_pk_mul_f32 v[80:81], v[78:79], v[80:81] op_sel_hi:[0,1]
	v_pk_mul_f32 v[82:83], v[78:79], v[82:83] op_sel_hi:[0,1]
	v_pk_mul_f32 v[80:81], v[8:9], v[80:81]
	v_pk_mul_f32 v[82:83], v[10:11], v[82:83]
	global_store_dwordx4 v[36:37], v[80:83], off offset:2048
	v_lshlrev_b32_e32 v84, 16, v66
	v_and_b32_e32 v85, 0xffff0000, v66
	v_lshlrev_b32_e32 v86, 16, v67
	v_and_b32_e32 v87, 0xffff0000, v67
	v_pk_mul_f32 v[84:85], v[78:79], v[84:85] op_sel_hi:[0,1]
	v_pk_mul_f32 v[86:87], v[78:79], v[86:87] op_sel_hi:[0,1]
	v_pk_mul_f32 v[84:85], v[12:13], v[84:85]
	v_pk_mul_f32 v[86:87], v[14:15], v[86:87]
	global_store_dwordx4 v[36:37], v[84:87], off offset:3072
	v_lshlrev_b32_e32 v80, 16, v68
	v_and_b32_e32 v81, 0xffff0000, v68
	v_lshlrev_b32_e32 v82, 16, v69
	v_and_b32_e32 v83, 0xffff0000, v69
	v_pk_mul_f32 v[80:81], v[78:79], v[80:81] op_sel_hi:[0,1]
	v_pk_mul_f32 v[82:83], v[78:79], v[82:83] op_sel_hi:[0,1]
	v_pk_mul_f32 v[80:81], v[16:17], v[80:81]
	v_pk_mul_f32 v[82:83], v[18:19], v[82:83]
	global_store_dwordx4 v[58:59], v[80:83], off
	v_lshlrev_b32_e32 v84, 16, v70
	v_and_b32_e32 v85, 0xffff0000, v70
	v_lshlrev_b32_e32 v86, 16, v71
	v_and_b32_e32 v87, 0xffff0000, v71
	v_pk_mul_f32 v[84:85], v[78:79], v[84:85] op_sel_hi:[0,1]
	v_pk_mul_f32 v[86:87], v[78:79], v[86:87] op_sel_hi:[0,1]
	v_pk_mul_f32 v[84:85], v[20:21], v[84:85]
	v_pk_mul_f32 v[86:87], v[22:23], v[86:87]
	global_store_dwordx4 v[58:59], v[84:87], off offset:1024
	v_lshlrev_b32_e32 v80, 16, v72
	v_and_b32_e32 v81, 0xffff0000, v72
	v_lshlrev_b32_e32 v82, 16, v73
	v_and_b32_e32 v83, 0xffff0000, v73
	v_pk_mul_f32 v[80:81], v[78:79], v[80:81] op_sel_hi:[0,1]
	v_pk_mul_f32 v[82:83], v[78:79], v[82:83] op_sel_hi:[0,1]
	v_pk_mul_f32 v[80:81], v[24:25], v[80:81]
	v_pk_mul_f32 v[82:83], v[26:27], v[82:83]
	global_store_dwordx4 v[58:59], v[80:83], off offset:2048
	v_lshlrev_b32_e32 v84, 16, v74
	v_and_b32_e32 v85, 0xffff0000, v74
	v_lshlrev_b32_e32 v86, 16, v75
	v_and_b32_e32 v87, 0xffff0000, v75
	v_pk_mul_f32 v[84:85], v[78:79], v[84:85] op_sel_hi:[0,1]
	v_pk_mul_f32 v[86:87], v[78:79], v[86:87] op_sel_hi:[0,1]
	v_pk_mul_f32 v[84:85], v[28:29], v[84:85]
	v_pk_mul_f32 v[86:87], v[30:31], v[86:87]
	global_store_dwordx4 v[58:59], v[84:87], off offset:3072
	v_lshl_add_u64 v[36:37], v[36:37], 0, s[6:7]
	v_lshl_add_u64 v[58:59], v[58:59], 0, s[6:7]
	s_sub_u32 s13, s13, 1
	s_branch .Lfn_loop
